# P1: prefetch next tile's first k-tile into LDS at epilogue start; drop compiler vmcnt(0)/(9) in tile prologue and PP epilogue
# speedup vs baseline: 1.0656x; 1.0027x over previous
.LBB0_107:
	s_or_b64 exec, exec, s[4:5]
	s_add_u32 s60, s76, 0x3eda000
	s_addc_u32 s61, s77, 0
	s_cmpk_gt_i32 s59, 0x4a3
	s_waitcnt lgkmcnt(0)
	s_barrier
	s_cbranch_scc1 .LBB0_120
	s_add_u32 s34, s76, 0x1180000
	s_addc_u32 s35, s77, 0
	v_mov_b32_e32 v131, 0
	s_mov_b64 s[4:5], 0x80
	s_mov_b64 s[6:7], 0x11c0080
	s_mov_b64 s[8:9], 0x100
	s_mov_b64 s[10:11], 0x1180100
	s_mov_b64 s[12:13], 0x40100
	s_mov_b64 s[14:15], 0x11c0100
	s_mov_b64 s[16:17], 0x180
	s_mov_b64 s[18:19], 0x1180180
	s_mov_b64 s[20:21], 0x40180
	s_movk_i32 s36, 0x2400
	v_mov_b32_e32 v144, 1
	s_mov_b32 s96, 0
	s_mov_b32 s37, s59
	s_branch .LBB0_110
.LBB0_109:
	v_or_b32_e32 v130, s24, v146
	v_add_u32_e32 v136, s25, v130
	v_or_b32_e32 v140, 16, v136
	v_ashrrev_i32_e32 v137, 31, v136
	v_ashrrev_i32_e32 v141, 31, v140
	v_lshl_add_u64 v[138:139], v[136:137], 2, s[2:3]
	v_lshl_add_u64 v[132:133], v[140:141], 2, s[2:3]
	global_load_dword v130, v[138:139], off
	global_load_dword v137, v[132:133], off
	global_load_dword v150, v[138:139], off offset:128
	global_load_dword v151, v[138:139], off offset:192
	global_load_dword v152, v[138:139], off offset:512
	global_load_dword v153, v[138:139], off offset:576
	global_load_dword v154, v[138:139], off offset:640
	global_load_dword v155, v[138:139], off offset:704
	v_or_b32_e32 v134, s22, v145
	v_or_b32_e32 v134, s23, v134
	v_mov_b64_e32 v[132:133], s[60:61]
	v_ashrrev_i32_e32 v135, 31, v134
	v_mad_i64_i32 v[142:143], s[22:23], v136, s36, v[132:133]
	v_lshlrev_b64 v[134:135], 1, v[134:135]
	v_mad_i64_i32 v[140:141], s[22:23], v140, s36, v[132:133]
	v_lshl_add_u64 v[142:143], v[142:143], 0, v[134:135]
	v_lshl_add_u64 v[140:141], v[140:141], 0, v[134:135]
	s_add_i32 s37, s37, s58
	s_cmpk_gt_i32 s37, 0x4a3
	s_cbranch_scc1 .Lp1pf_last
	s_mov_b32 s96, 1
	s_and_b32 s27, s37, 7
	s_lshr_b32 s26, s37, 3
	s_mul_i32 s28, s27, 0x95
	s_mul_i32 s29, s27, 0x94
	s_add_i32 s29, s29, 4
	s_cmp_gt_u32 s27, 3
	s_cselect_b32 s28, s29, s28
	s_add_i32 s26, s28, s26
	s_mul_hi_u32 s27, s26, 0x38e38e39
	s_lshr_b32 s27, s27, 5
	s_mul_i32 s28, s27, 0x90
	s_sub_i32 s26, s26, s28
	s_cmp_lt_u32 s27, 8
	s_cselect_b32 s28, 3, 1
	s_cselect_b32 s29, 7, 1
	s_lshr_b32 s30, s26, s28
	s_and_b32 s26, s26, s29
	s_lshl_b32 s27, s27, 3
	s_add_i32 s26, s26, s27
	s_lshl_b32 s26, s26, 19
	s_lshl_b32 s28, s30, 19
	s_add_u32 s26, s34, s26
	s_addc_u32 s27, s35, 0
	s_add_u32 s28, s76, s28
	s_addc_u32 s29, s77, 0
	s_add_u32 s42, s28, 0x40000
	s_addc_u32 s43, s29, 0
	s_add_u32 s50, s26, 0x40000
	s_addc_u32 s51, s27, 0
	s_add_i32 m0, s40, 0x10000
	s_nop 0
	global_load_lds_dwordx4 v243, s[28:29]
	s_add_i32 m0, s40, 0x12000
	s_nop 0
	global_load_lds_dwordx4 v244, s[28:29]
	s_add_i32 m0, s40, 0
	s_nop 0
	global_load_lds_dwordx4 v245, s[26:27]
	s_add_i32 m0, s40, 0x2000
	s_nop 0
	global_load_lds_dwordx4 v246, s[26:27]
	s_add_i32 m0, s40, 0x14000
	s_nop 0
	global_load_lds_dwordx4 v243, s[42:43]
	s_add_i32 m0, s40, 0x16000
	s_nop 0
	global_load_lds_dwordx4 v244, s[42:43]
	s_add_i32 m0, s40, 0x4000
	s_nop 0
	global_load_lds_dwordx4 v245, s[50:51]
	s_add_i32 m0, s40, 0x6000
	s_nop 0
	global_load_lds_dwordx4 v246, s[50:51]
	s_branch .Lp1pf_done
.Lp1pf_last:
	global_load_dword v247, v[138:139], off
	global_load_dword v247, v[138:139], off
	global_load_dword v247, v[138:139], off
	global_load_dword v247, v[138:139], off
	global_load_dword v247, v[138:139], off
	global_load_dword v247, v[138:139], off
	global_load_dword v247, v[138:139], off
	global_load_dword v247, v[138:139], off
.Lp1pf_done:
	s_cmpk_gt_i32 s37, 0x4a3
	s_waitcnt vmcnt(14)
	v_mul_f32_e32 v120, v120, v130
	v_mul_f32_e32 v121, v121, v130
	v_mul_f32_e32 v117, v117, v130
	v_mul_f32_e32 v122, v122, v130
	v_mul_f32_e32 v123, v123, v130
	v_mul_f32_e32 v124, v124, v130
	v_mul_f32_e32 v101, v101, v137
	v_mul_f32_e32 v118, v118, v130
	v_mul_f32_e32 v119, v119, v130
	v_mul_f32_e32 v145, v114, v130
	v_mul_f32_e32 v146, v115, v130
	v_mul_f32_e32 v147, v116, v130
	v_mul_f32_e32 v125, v125, v130
	v_cvt_pk_bf16_f32 v114, v118, v119
	v_cvt_pk_bf16_f32 v115, v120, v121
	v_cvt_pk_bf16_f32 v116, v145, v146
	v_cvt_pk_bf16_f32 v117, v147, v117
	v_cvt_pk_bf16_f32 v120, v122, v123
	v_cvt_pk_bf16_f32 v121, v124, v125
	v_mul_f32_e32 v102, v102, v137
	v_mul_f32_e32 v103, v103, v137
	v_mul_f32_e32 v104, v104, v137
	v_mul_f32_e32 v105, v105, v137
	v_mul_f32_e32 v122, v98, v137
	v_mul_f32_e32 v123, v99, v137
	v_mul_f32_e32 v124, v100, v137
	v_cvt_pk_bf16_f32 v98, v102, v103
	v_cvt_pk_bf16_f32 v99, v104, v105
	v_cvt_pk_bf16_f32 v100, v122, v123
	v_cvt_pk_bf16_f32 v101, v124, v101
	v_mul_f32_e32 v126, v126, v130
	v_mul_f32_e32 v127, v127, v130
	v_mul_f32_e32 v128, v128, v130
	v_mul_f32_e32 v129, v129, v130
	v_cvt_pk_bf16_f32 v118, v126, v127
	v_cvt_pk_bf16_f32 v119, v128, v129
	v_mul_f32_e32 v110, v110, v137
	v_mul_f32_e32 v111, v111, v137
	v_mul_f32_e32 v112, v112, v137
	v_mul_f32_e32 v113, v113, v137
	v_mul_f32_e32 v106, v106, v137
	v_mul_f32_e32 v107, v107, v137
	v_mul_f32_e32 v108, v108, v137
	v_mul_f32_e32 v109, v109, v137
	global_store_dwordx4 v[142:143], v[114:117], off
	global_store_dwordx4 v[142:143], v[118:121], off offset:256
	v_cvt_pk_bf16_f32 v102, v110, v111
	v_cvt_pk_bf16_f32 v103, v112, v113
	v_cvt_pk_bf16_f32 v104, v106, v107
	v_cvt_pk_bf16_f32 v105, v108, v109
	global_store_dwordx4 v[140:141], v[98:101], off
	global_store_dwordx4 v[140:141], v[102:105], off offset:256
	v_or_b32_e32 v98, 48, v136
	v_ashrrev_i32_e32 v99, 31, v98
	v_lshl_add_u64 v[100:101], v[98:99], 2, s[2:3]
	v_or_b32_e32 v99, 32, v136
	v_add_u32_e32 v100, 0x80, v136
	v_mad_i64_i32 v[102:103], s[22:23], v99, s36, v[132:133]
	v_mad_i64_i32 v[98:99], s[22:23], v98, s36, v[132:133]
	v_ashrrev_i32_e32 v101, 31, v100
	v_lshl_add_u64 v[102:103], v[102:103], 0, v[134:135]
	v_lshl_add_u64 v[98:99], v[98:99], 0, v[134:135]
	v_lshl_add_u64 v[104:105], v[100:101], 2, s[2:3]
	s_waitcnt vmcnt(16)
	v_mul_f32_e32 v78, v78, v150
	v_mul_f32_e32 v79, v79, v150
	v_mul_f32_e32 v80, v80, v150
	v_mul_f32_e32 v81, v81, v150
	v_mul_f32_e32 v74, v74, v150
	v_mul_f32_e32 v75, v75, v150
	v_mul_f32_e32 v76, v76, v150
	v_mul_f32_e32 v77, v77, v150
	s_waitcnt vmcnt(16)
	v_mul_f32_e32 v110, v66, v151
	v_mul_f32_e32 v111, v67, v151
	v_mul_f32_e32 v112, v68, v151
	v_mul_f32_e32 v113, v69, v151
	v_cvt_pk_bf16_f32 v66, v78, v79
	v_cvt_pk_bf16_f32 v67, v80, v81
	v_cvt_pk_bf16_f32 v68, v74, v75
	v_cvt_pk_bf16_f32 v69, v76, v77
	v_mul_f32_e32 v94, v94, v150
	v_mul_f32_e32 v95, v95, v150
	v_mul_f32_e32 v96, v96, v150
	v_mul_f32_e32 v97, v97, v150
	v_mul_f32_e32 v90, v90, v150
	v_mul_f32_e32 v91, v91, v150
	v_mul_f32_e32 v92, v92, v150
	v_mul_f32_e32 v93, v93, v150
	v_mul_f32_e32 v101, v70, v151
	v_mul_f32_e32 v106, v71, v151
	v_mul_f32_e32 v108, v72, v151
	v_mul_f32_e32 v109, v73, v151
	v_mul_f32_e32 v86, v86, v151
	v_mul_f32_e32 v87, v87, v151
	v_mul_f32_e32 v88, v88, v151
	v_mul_f32_e32 v89, v89, v151
	v_mul_f32_e32 v82, v82, v151
	v_mul_f32_e32 v83, v83, v151
	v_mul_f32_e32 v84, v84, v151
	v_mul_f32_e32 v85, v85, v151
	v_cvt_pk_bf16_f32 v70, v94, v95
	v_cvt_pk_bf16_f32 v71, v96, v97
	v_cvt_pk_bf16_f32 v72, v90, v91
	v_cvt_pk_bf16_f32 v73, v92, v93
	v_cvt_pk_bf16_f32 v74, v101, v106
	v_cvt_pk_bf16_f32 v75, v108, v109
	v_cvt_pk_bf16_f32 v76, v110, v111
	v_cvt_pk_bf16_f32 v77, v112, v113
	v_cvt_pk_bf16_f32 v78, v86, v87
	v_cvt_pk_bf16_f32 v79, v88, v89
	v_cvt_pk_bf16_f32 v80, v82, v83
	v_cvt_pk_bf16_f32 v81, v84, v85
	global_store_dwordx4 v[102:103], v[66:69], off
	global_store_dwordx4 v[102:103], v[70:73], off offset:256
	global_store_dwordx4 v[98:99], v[74:77], off
	global_store_dwordx4 v[98:99], v[78:81], off offset:256
	v_add_u32_e32 v66, 0x90, v136
	v_ashrrev_i32_e32 v67, 31, v66
	v_lshl_add_u64 v[68:69], v[66:67], 2, s[2:3]
	v_add_u32_e32 v68, 0xa0, v136
	v_mad_i64_i32 v[70:71], s[22:23], v100, s36, v[132:133]
	v_mad_i64_i32 v[66:67], s[22:23], v66, s36, v[132:133]
	v_ashrrev_i32_e32 v69, 31, v68
	v_lshl_add_u64 v[70:71], v[70:71], 0, v[134:135]
	v_lshl_add_u64 v[66:67], v[66:67], 0, v[134:135]
	v_lshl_add_u64 v[72:73], v[68:69], 2, s[2:3]
	s_waitcnt vmcnt(18)
	v_mul_f32_e32 v54, v54, v152
	v_mul_f32_e32 v55, v55, v152
	v_mul_f32_e32 v56, v56, v152
	v_mul_f32_e32 v57, v57, v152
	v_mul_f32_e32 v46, v46, v152
	v_mul_f32_e32 v47, v47, v152
	v_mul_f32_e32 v48, v48, v152
	v_mul_f32_e32 v49, v49, v152
	s_waitcnt vmcnt(18)
	v_mul_f32_e32 v78, v34, v153
	v_mul_f32_e32 v79, v35, v153
	v_mul_f32_e32 v80, v36, v153
	v_mul_f32_e32 v81, v37, v153
	v_cvt_pk_bf16_f32 v34, v54, v55
	v_cvt_pk_bf16_f32 v35, v56, v57
	v_cvt_pk_bf16_f32 v36, v46, v47
	v_cvt_pk_bf16_f32 v37, v48, v49
	v_mul_f32_e32 v62, v62, v152
	v_mul_f32_e32 v63, v63, v152
	v_mul_f32_e32 v64, v64, v152
	v_mul_f32_e32 v65, v65, v152
	v_mul_f32_e32 v58, v58, v152
	v_mul_f32_e32 v59, v59, v152
	v_mul_f32_e32 v60, v60, v152
	v_mul_f32_e32 v61, v61, v152
	v_mul_f32_e32 v69, v38, v153
	v_mul_f32_e32 v74, v39, v153
	v_mul_f32_e32 v76, v40, v153
	v_mul_f32_e32 v77, v41, v153
	v_mul_f32_e32 v50, v50, v153
	v_mul_f32_e32 v51, v51, v153
	v_mul_f32_e32 v52, v52, v153
	v_mul_f32_e32 v53, v53, v153
	v_mul_f32_e32 v82, v42, v153
	v_mul_f32_e32 v83, v43, v153
	v_mul_f32_e32 v84, v44, v153
	v_mul_f32_e32 v75, v45, v153
	v_cvt_pk_bf16_f32 v38, v62, v63
	v_cvt_pk_bf16_f32 v39, v64, v65
	v_cvt_pk_bf16_f32 v40, v58, v59
	v_cvt_pk_bf16_f32 v41, v60, v61
	v_cvt_pk_bf16_f32 v42, v69, v74
	v_cvt_pk_bf16_f32 v43, v76, v77
	v_cvt_pk_bf16_f32 v44, v78, v79
	v_cvt_pk_bf16_f32 v45, v80, v81
	v_cvt_pk_bf16_f32 v46, v50, v51
	v_cvt_pk_bf16_f32 v47, v52, v53
	v_cvt_pk_bf16_f32 v48, v82, v83
	v_cvt_pk_bf16_f32 v49, v84, v75
	global_store_dwordx4 v[70:71], v[34:37], off
	global_store_dwordx4 v[70:71], v[38:41], off offset:256
	global_store_dwordx4 v[66:67], v[42:45], off
	global_store_dwordx4 v[66:67], v[46:49], off offset:256
	v_add_u32_e32 v34, 0xb0, v136
	v_ashrrev_i32_e32 v35, 31, v34
	v_lshl_add_u64 v[36:37], v[34:35], 2, s[2:3]
	v_mad_i64_i32 v[36:37], s[22:23], v68, s36, v[132:133]
	v_mad_i64_i32 v[34:35], s[22:23], v34, s36, v[132:133]
	v_lshl_add_u64 v[36:37], v[36:37], 0, v[134:135]
	v_lshl_add_u64 v[34:35], v[34:35], 0, v[134:135]
	s_waitcnt vmcnt(20)
	v_mul_f32_e32 v22, v22, v154
	v_mul_f32_e32 v23, v23, v154
	v_mul_f32_e32 v24, v24, v154
	v_mul_f32_e32 v25, v25, v154
	v_mul_f32_e32 v14, v14, v154
	v_mul_f32_e32 v15, v15, v154
	v_mul_f32_e32 v16, v16, v154
	v_mul_f32_e32 v17, v17, v154
	s_waitcnt vmcnt(20)
	v_mul_f32_e32 v43, v2, v155
	v_mul_f32_e32 v44, v3, v155
	v_mul_f32_e32 v45, v4, v155
	v_mul_f32_e32 v46, v5, v155
	v_cvt_pk_bf16_f32 v2, v22, v23
	v_cvt_pk_bf16_f32 v3, v24, v25
	v_cvt_pk_bf16_f32 v4, v14, v15
	v_cvt_pk_bf16_f32 v5, v16, v17
	v_mul_f32_e32 v30, v30, v154
	v_mul_f32_e32 v31, v31, v154
	v_mul_f32_e32 v32, v32, v154
	v_mul_f32_e32 v33, v33, v154
	v_mul_f32_e32 v26, v26, v154
	v_mul_f32_e32 v27, v27, v154
	v_mul_f32_e32 v28, v28, v154
	v_mul_f32_e32 v29, v29, v154
	v_mul_f32_e32 v38, v6, v155
	v_mul_f32_e32 v40, v7, v155
	v_mul_f32_e32 v41, v8, v155
	v_mul_f32_e32 v42, v9, v155
	v_mul_f32_e32 v18, v18, v155
	v_mul_f32_e32 v19, v19, v155
	v_mul_f32_e32 v20, v20, v155
	v_mul_f32_e32 v21, v21, v155
	v_mul_f32_e32 v47, v10, v155
	v_mul_f32_e32 v48, v11, v155
	v_mul_f32_e32 v49, v12, v155
	v_mul_f32_e32 v39, v13, v155
	v_cvt_pk_bf16_f32 v6, v30, v31
	v_cvt_pk_bf16_f32 v7, v32, v33
	v_cvt_pk_bf16_f32 v8, v26, v27
	v_cvt_pk_bf16_f32 v9, v28, v29
	v_cvt_pk_bf16_f32 v10, v38, v40
	v_cvt_pk_bf16_f32 v11, v41, v42
	v_cvt_pk_bf16_f32 v12, v43, v44
	v_cvt_pk_bf16_f32 v13, v45, v46
	v_cvt_pk_bf16_f32 v14, v18, v19
	v_cvt_pk_bf16_f32 v15, v20, v21
	v_cvt_pk_bf16_f32 v16, v47, v48
	v_cvt_pk_bf16_f32 v17, v49, v39
	global_store_dwordx4 v[36:37], v[2:5], off
	global_store_dwordx4 v[36:37], v[6:9], off offset:256
	global_store_dwordx4 v[34:35], v[10:13], off
	global_store_dwordx4 v[34:35], v[14:17], off offset:256
	s_barrier
	s_cbranch_scc1 .LBB0_120

.LBB0_114:
	s_add_i32 s46, s25, s22
	s_mul_hi_i32 s22, s46, 0x38e38e39
	s_lshr_b32 s23, s22, 31
	s_ashr_i32 s47, s22, 5
	s_add_i32 s47, s47, s23
	s_lshl_b32 s24, s47, 3
	s_sub_i32 s22, 0x42, s24
	s_min_u32 s25, s22, 8
	s_mul_i32 s48, s47, 0x90
	s_sub_i32 s26, s46, s48
	v_cvt_f32_ubyte0_e32 v3, s25
	v_cvt_f32_i32_e32 v2, s26
	v_rcp_iflag_f32_e32 v4, v3
	s_ashr_i32 s22, s26, 30
	v_mov_b32_e32 v26, v0
	s_or_b32 s27, s22, 1
	v_mul_f32_e32 v4, v2, v4
	v_trunc_f32_e32 v4, v4
	v_fma_f32 v2, -v4, v3, v2
	v_cmp_ge_f32_e64 s[22:23], |v2|, v3
	v_cvt_i32_f32_e32 v4, v4
	v_ashrrev_i32_e32 v3, 31, v26
	v_lshrrev_b32_e32 v3, 26, v3
	v_add_u32_e32 v3, v26, v3
	v_ashrrev_i32_e32 v12, 6, v3
	v_bfe_i32 v3, v26, 27, 1
	v_lshlrev_b32_e32 v2, 4, v26
	v_lshrrev_b32_e32 v3, 22, v3
	v_add_u32_e32 v3, v2, v3
	v_and_b32_e32 v3, 0xfffffc00, v3
	s_and_b64 s[22:23], s[22:23], exec
	v_sub_u32_e32 v3, v2, v3
	v_readfirstlane_b32 s23, v4
	v_lshrrev_b32_e32 v4, 4, v3
	v_bitop3_b32 v4, v4, v3, 32 bitop3:0x6c
	v_ashrrev_i32_e32 v3, 31, v3
	v_lshrrev_b32_e32 v3, 26, v3
	v_add_u32_e32 v3, v4, v3
	v_ashrrev_i32_e32 v17, 6, v3
	v_lshlrev_b32_e32 v5, 3, v12
	v_mul_i32_i24_e32 v6, 64, v17
	v_and_b32_e32 v5, -16, v5
	v_sub_u32_e32 v4, v4, v6
	v_add_u32_e32 v3, v17, v5
	v_lshlrev_b32_e32 v5, 5, v12
	v_ashrrev_i16_sdwa v4, v144, sext(v4) dst_sel:DWORD dst_unused:UNUSED_PAD src0_sel:DWORD src1_sel:BYTE_0
	v_and_b32_e32 v5, 32, v5
	v_bfe_i32 v18, v4, 0, 16
	v_lshlrev_b32_e32 v4, 1, v3
	v_add_lshl_u32 v5, v5, v18, 1
	v_add_u32_e32 v2, 0x2000, v2
	v_and_b32_e32 v13, 0x1fffe0, v3
	v_and_b32_e32 v14, 24, v4
	v_lshrrev_b32_e32 v4, 2, v3
	v_lshl_add_u32 v132, v3, 11, v5
	v_ashrrev_i32_e32 v3, 31, v2
	v_lshrrev_b32_e32 v3, 22, v3
	v_add_u32_e32 v3, v2, v3
	v_ashrrev_i32_e32 v19, 10, v3
	v_mul_i32_i24_e32 v3, 0x400, v19
	s_cselect_b32 s22, s27, 0
	v_and_b32_e32 v16, 3, v17
	v_sub_u32_e32 v2, v2, v3
	s_add_i32 s49, s23, s22
	v_and_b32_e32 v15, 4, v4
	v_or_b32_e32 v4, v13, v16
	v_lshrrev_b32_e32 v3, 4, v2
	s_sext_i32_i16 s22, s49
	s_mul_i32 s49, s49, s25
	v_or3_b32 v4, v4, v14, v15
	v_bitop3_b32 v2, v3, v2, 32 bitop3:0x6c
	s_sub_i32 s23, s26, s49
	v_lshl_add_u32 v130, v4, 11, v5
	v_ashrrev_i32_e32 v4, 31, v2
	s_sext_i32_i16 s23, s23
	v_lshrrev_b32_e32 v4, 26, v4
	s_add_i32 s24, s24, s23
	v_add_u32_e32 v4, v2, v4
	s_lshl_b32 s24, s24, 8
	s_lshl_b32 s22, s22, 8
	v_readfirstlane_b32 s38, v26
	v_lshlrev_b32_e32 v3, 3, v19
	v_ashrrev_i32_e32 v24, 6, v4
	v_and_b32_e32 v4, 0xc0, v4
	v_and_b32_e32 v3, -16, v3
	v_sub_u32_e32 v2, v2, v4
	s_ashr_i32 s45, s38, 6
	s_ashr_i32 s25, s24, 31
	s_ashr_i32 s23, s22, 31
	s_ashr_i32 s44, s38, 8
	v_add_u32_e32 v3, v24, v3
	v_ashrrev_i16_sdwa v2, v144, sext(v2) dst_sel:DWORD dst_unused:UNUSED_PAD src0_sel:DWORD src1_sel:BYTE_0
	s_lshl_b32 s39, s45, 10
	s_lshl_b64 s[26:27], s[24:25], 11
	s_lshl_b64 s[30:31], s[22:23], 11
	v_bfe_i32 v25, v2, 0, 16
	v_lshlrev_b32_e32 v2, 1, v3
	s_add_u32 s28, s76, s30
	v_lshlrev_b32_e32 v5, 5, v19
	v_and_b32_e32 v20, 0x1fffe0, v3
	v_and_b32_e32 v21, 24, v2
	v_lshrrev_b32_e32 v2, 2, v3
	v_and_b32_e32 v23, 3, v24
	s_addc_u32 s29, s77, s31
	s_add_i32 s40, s39, 0
	v_and_b32_e32 v5, 32, v5
	v_and_b32_e32 v22, 4, v2
	v_or_b32_e32 v2, v20, v23
	s_add_i32 m0, s40, 0x10000
	v_or3_b32 v2, v2, v21, v22
	v_add_lshl_u32 v4, v5, v25, 1
	s_add_i32 m0, s40, 0x12000
	v_lshl_add_u32 v2, v2, 11, v4
	s_add_u32 s26, s34, s26
	s_addc_u32 s27, s35, s27
	s_mov_b32 m0, s40
	s_add_i32 s41, s40, 0x2000
	v_lshl_add_u32 v134, v3, 11, v4
	s_mov_b32 m0, s41
	s_add_u32 s42, s28, 0x40000
	s_addc_u32 s43, s29, 0
	s_add_i32 m0, s40, 0x14000
	v_mov_b32_e32 v3, v131
	s_add_i32 m0, s40, 0x16000
	s_add_u32 s50, s26, 0x40000
	s_addc_u32 s51, s27, 0
	s_add_i32 s42, s40, 0x4000
	s_mov_b32 m0, s42
	s_add_i32 s43, s40, 0x6000
	s_mov_b32 m0, s43
	v_mov_b32_e32 v133, v131
	v_mov_b32_e32 v243, v130
	v_mov_b32_e32 v244, v2
	v_mov_b32_e32 v245, v132
	v_mov_b32_e32 v246, v134
	s_cmp_eq_u32 s96, 1
	s_cbranch_scc1 .Lp1pf_have
	s_add_u32 s42, s28, 0x40000
	s_addc_u32 s43, s29, 0
	s_add_i32 m0, s40, 0x10000
	s_nop 0
	global_load_lds_dwordx4 v130, s[28:29]
	s_add_i32 m0, s40, 0x12000
	s_nop 0
	global_load_lds_dwordx4 v2, s[28:29]
	s_add_i32 m0, s40, 0
	s_nop 0
	global_load_lds_dwordx4 v132, s[26:27]
	s_add_i32 m0, s40, 0x2000
	s_nop 0
	global_load_lds_dwordx4 v134, s[26:27]
	s_add_i32 m0, s40, 0x14000
	s_nop 0
	global_load_lds_dwordx4 v130, s[42:43]
	s_add_i32 m0, s40, 0x16000
	s_nop 0
	global_load_lds_dwordx4 v2, s[42:43]
	s_add_i32 m0, s40, 0x4000
	s_nop 0
	global_load_lds_dwordx4 v132, s[50:51]
	s_add_i32 m0, s40, 0x6000
	s_nop 0
	global_load_lds_dwordx4 v134, s[50:51]
	s_add_i32 s42, s40, 0x4000
	s_add_i32 s43, s40, 0x6000
	s_waitcnt vmcnt(4)
	s_branch .Lp1pf_join
.Lp1pf_have:
	s_waitcnt vmcnt(16)
.Lp1pf_join:
	v_mov_b32_e32 v135, v131
	v_lshl_add_u64 v[10:11], s[28:29], 0, v[130:131]
	v_lshl_add_u64 v[8:9], s[28:29], 0, v[2:3]
	v_lshl_add_u64 v[6:7], s[26:27], 0, v[132:133]
	s_cmp_lg_u32 s44, 1
	v_lshl_add_u64 v[4:5], s[26:27], 0, v[134:135]
	s_cbranch_scc1 .LBB0_116
	s_barrier
.LBB0_116:
	v_lshrrev_b32_e32 v27, 1, v26
	v_and_b32_e32 v145, 24, v27
	s_lshl_b32 s23, s45, 5
	v_and_b32_e32 v146, 15, v26
	v_lshlrev_b32_e32 v27, 1, v145
	v_lshlrev_b32_e32 v26, 2, v26
	s_and_b32 s23, s23, 0x60
	s_lshl_b32 s25, s44, 6
	v_lshl_or_b32 v27, v146, 6, v27
	v_and_b32_e32 v26, 32, v26
	s_lshl_b32 s44, s44, 13
	s_lshl_b32 s45, s23, 7
	s_add_i32 m0, s40, 0x18000
	v_lshl_add_u64 v[10:11], v[10:11], 0, s[4:5]
	v_bitop3_b32 v148, v27, s45, v26 bitop3:0xde
	v_bitop3_b32 v26, v27, s44, v26 bitop3:0xde
	s_barrier
	global_load_lds_dwordx4 v[10:11], off
	v_lshl_add_u64 v[8:9], v[8:9], 0, s[4:5]
	s_add_i32 m0, s40, 0x1a000
	s_add_i32 s44, s40, 0x8000
	s_add_i32 s45, s40, 0xa000
	global_load_lds_dwordx4 v[8:9], off
	v_lshl_add_u64 v[6:7], v[6:7], 0, s[4:5]
	s_mov_b32 m0, s44
	s_add_u32 s28, s28, 0x40080
	global_load_lds_dwordx4 v[6:7], off
	v_lshl_add_u64 v[4:5], v[4:5], 0, s[4:5]
	s_mov_b32 m0, s45
	s_addc_u32 s29, s29, 0
	global_load_lds_dwordx4 v[4:5], off
	s_add_i32 m0, s40, 0x1c000
	v_lshl_add_u64 v[4:5], s[28:29], 0, v[130:131]
	global_load_lds_dwordx4 v[4:5], off
	v_lshl_add_u64 v[2:3], s[28:29], 0, v[2:3]
	s_add_i32 m0, s40, 0x1e000
	s_sub_i32 s29, s46, s49
	global_load_lds_dwordx4 v[2:3], off
	v_lshlrev_b32_e32 v2, 14, v12
	v_and_b32_e32 v2, 0xffff8000, v2
	v_and_b32_e32 v3, 1, v12
	s_sub_i32 s29, s29, s48
	v_lshl_add_u32 v2, v17, 11, v2
	v_lshlrev_b32_e32 v3, 6, v3
	s_sext_i32_i16 s29, s29
	v_or_b32_e32 v2, v2, v3
	v_lshlrev_b32_e32 v4, 1, v18
	s_lshl_b32 s28, s47, 11
	s_lshl_b32 s29, s29, 8
	v_add_u32_e32 v130, v2, v4
	v_lshlrev_b32_e32 v2, 14, v19
	s_add_i32 s28, s28, s29
	v_and_b32_e32 v2, 0xffff8000, v2
	v_and_b32_e32 v5, 1, v19
	s_ashr_i32 s29, s28, 31
	v_lshl_add_u32 v2, v24, 11, v2
	v_lshlrev_b32_e32 v5, 6, v5
	s_lshl_b64 s[28:29], s[28:29], 11
	v_or_b32_e32 v2, v2, v5
	v_lshlrev_b32_e32 v6, 1, v25
	v_lshl_add_u64 v[136:137], s[28:29], 0, v[130:131]
	v_add_u32_e32 v130, v2, v6
	v_add_u32_e32 v2, v13, v14
	v_add3_u32 v2, v2, v15, v16
	v_lshl_or_b32 v2, v2, 11, v3
	v_lshl_add_u64 v[138:139], s[28:29], 0, v[130:131]
	v_add_u32_e32 v130, v2, v4
	v_add_u32_e32 v2, v20, v21
	v_add3_u32 v2, v2, v22, v23
	s_waitcnt vmcnt(6)
	v_lshl_or_b32 v2, v2, 11, v5
	v_lshl_add_u64 v[140:141], s[30:31], 0, v[130:131]
	v_add_u32_e32 v130, v2, v6
	v_mov_b32_e32 v2, 0
	s_mov_b32 s46, -2
	v_add_u32_e32 v147, 0, v26
	s_mov_b64 s[28:29], s[76:77]
	v_mov_b32_e32 v3, v2
	v_mov_b32_e32 v4, v2
	v_mov_b32_e32 v5, v2
	v_mov_b32_e32 v6, v2
	v_mov_b32_e32 v7, v2
	v_mov_b32_e32 v8, v2
	v_mov_b32_e32 v9, v2
	v_mov_b32_e32 v10, v2
	v_mov_b32_e32 v11, v2
	v_mov_b32_e32 v12, v2
	v_mov_b32_e32 v13, v2
	v_mov_b32_e32 v14, v2
	v_mov_b32_e32 v15, v2
	v_mov_b32_e32 v16, v2
	v_mov_b32_e32 v17, v2
	v_mov_b32_e32 v18, v2
	v_mov_b32_e32 v19, v2
	v_mov_b32_e32 v20, v2
	v_mov_b32_e32 v21, v2
	v_mov_b32_e32 v22, v2
	v_mov_b32_e32 v23, v2
	v_mov_b32_e32 v24, v2
	v_mov_b32_e32 v25, v2
	v_mov_b32_e32 v26, v2
	v_mov_b32_e32 v27, v2
	v_mov_b32_e32 v28, v2
	v_mov_b32_e32 v29, v2
	v_mov_b32_e32 v30, v2
	v_mov_b32_e32 v31, v2
	v_mov_b32_e32 v32, v2
	v_mov_b32_e32 v33, v2
	v_mov_b32_e32 v34, v2
	v_mov_b32_e32 v35, v2
	v_mov_b32_e32 v36, v2
	v_mov_b32_e32 v37, v2
	v_mov_b32_e32 v38, v2
	v_mov_b32_e32 v39, v2
	v_mov_b32_e32 v40, v2
	v_mov_b32_e32 v41, v2
	v_mov_b32_e32 v42, v2
	v_mov_b32_e32 v43, v2
	v_mov_b32_e32 v44, v2
	v_mov_b32_e32 v45, v2
	v_mov_b32_e32 v46, v2
	v_mov_b32_e32 v47, v2
	v_mov_b32_e32 v48, v2
	v_mov_b32_e32 v49, v2
	v_mov_b32_e32 v50, v2
	v_mov_b32_e32 v51, v2
	v_mov_b32_e32 v52, v2
	v_mov_b32_e32 v53, v2
	v_mov_b32_e32 v54, v2
	v_mov_b32_e32 v55, v2
	v_mov_b32_e32 v56, v2
	v_mov_b32_e32 v57, v2
	v_mov_b32_e32 v58, v2
	v_mov_b32_e32 v59, v2
	v_mov_b32_e32 v60, v2
	v_mov_b32_e32 v61, v2
	v_mov_b32_e32 v62, v2
	v_mov_b32_e32 v63, v2
	v_mov_b32_e32 v64, v2
	v_mov_b32_e32 v65, v2
	v_mov_b32_e32 v66, v2
	v_mov_b32_e32 v67, v2
	v_mov_b32_e32 v68, v2
	v_mov_b32_e32 v69, v2
	v_mov_b32_e32 v70, v2
	v_mov_b32_e32 v71, v2
	v_mov_b32_e32 v72, v2
	v_mov_b32_e32 v73, v2
	v_mov_b32_e32 v74, v2
	v_mov_b32_e32 v75, v2
	v_mov_b32_e32 v76, v2
	v_mov_b32_e32 v77, v2
	v_mov_b32_e32 v78, v2
	v_mov_b32_e32 v79, v2
	v_mov_b32_e32 v80, v2
	v_mov_b32_e32 v81, v2
	v_mov_b32_e32 v82, v2
	v_mov_b32_e32 v83, v2
	v_mov_b32_e32 v84, v2
	v_mov_b32_e32 v85, v2
	v_mov_b32_e32 v86, v2
	v_mov_b32_e32 v87, v2
	v_mov_b32_e32 v88, v2
	v_mov_b32_e32 v89, v2
	v_mov_b32_e32 v90, v2
	v_mov_b32_e32 v91, v2
	v_mov_b32_e32 v92, v2
	v_mov_b32_e32 v93, v2
	v_mov_b32_e32 v94, v2
	v_mov_b32_e32 v95, v2
	v_mov_b32_e32 v96, v2
	v_mov_b32_e32 v97, v2
	v_mov_b32_e32 v98, v2
	v_mov_b32_e32 v99, v2
	v_mov_b32_e32 v100, v2
	v_mov_b32_e32 v101, v2
	v_mov_b32_e32 v102, v2
	v_mov_b32_e32 v103, v2
	v_mov_b32_e32 v104, v2
	v_mov_b32_e32 v105, v2
	v_mov_b32_e32 v106, v2
	v_mov_b32_e32 v107, v2
	v_mov_b32_e32 v108, v2
	v_mov_b32_e32 v109, v2
	v_mov_b32_e32 v110, v2
	v_mov_b32_e32 v111, v2
	v_mov_b32_e32 v112, v2
	v_mov_b32_e32 v113, v2
	v_mov_b32_e32 v114, v2
	v_mov_b32_e32 v115, v2
	v_mov_b32_e32 v116, v2
	v_mov_b32_e32 v117, v2
	v_mov_b32_e32 v118, v2
	v_mov_b32_e32 v119, v2
	v_mov_b32_e32 v120, v2
	v_mov_b32_e32 v121, v2
	v_mov_b32_e32 v122, v2
	v_mov_b32_e32 v123, v2
	v_mov_b32_e32 v124, v2
	v_mov_b32_e32 v125, v2
	v_mov_b32_e32 v126, v2
	v_mov_b32_e32 v127, v2
	v_mov_b32_e32 v128, v2
	v_mov_b32_e32 v129, v2
	v_lshl_add_u64 v[142:143], s[30:31], 0, v[130:131]
	s_barrier

.LBB0_122:
	s_lshl_b32 s13, s26, 6
	v_or_b32_e32 v130, s12, v132
	v_add_u32_e32 v132, s13, v130
	v_or_b32_e32 v130, s10, v133
	v_or_b32_e32 v136, s11, v130
	v_or_b32_e32 v138, 16, v132
	v_ashrrev_i32_e32 v133, 31, v132
	v_ashrrev_i32_e32 v139, 31, v138
	v_cvt_pk_bf16_f32 v122, v122, v123
	v_cvt_pk_bf16_f32 v123, v124, v125
	v_cvt_pk_bf16_f32 v124, v114, v115
	v_lshlrev_b64 v[114:115], 11, v[132:133]
	v_ashrrev_i32_e32 v137, 31, v136
	v_cvt_pk_bf16_f32 v125, v116, v117
	v_lshl_add_u64 v[116:117], s[2:3], 0, v[114:115]
	v_lshlrev_b64 v[114:115], 1, v[136:137]
	v_cvt_pk_bf16_f32 v102, v102, v103
	v_cvt_pk_bf16_f32 v103, v104, v105
	v_cvt_pk_bf16_f32 v104, v98, v99
	v_lshlrev_b64 v[98:99], 11, v[138:139]
	v_lshl_add_u64 v[136:137], v[116:117], 0, v[114:115]
	v_cvt_pk_bf16_f32 v116, v126, v127
	v_cvt_pk_bf16_f32 v117, v128, v129
	v_lshl_add_u64 v[98:99], s[2:3], 0, v[98:99]
	v_cvt_pk_bf16_f32 v118, v118, v119
	v_cvt_pk_bf16_f32 v119, v120, v121
	global_store_dwordx4 v[136:137], v[116:119], off offset:256
	v_cvt_pk_bf16_f32 v105, v100, v101
	v_cvt_pk_bf16_f32 v100, v106, v107
	v_cvt_pk_bf16_f32 v101, v108, v109
	v_cvt_pk_bf16_f32 v86, v86, v87
	v_cvt_pk_bf16_f32 v87, v88, v89
	s_nop 1
	v_lshl_add_u64 v[116:117], v[98:99], 0, v[114:115]
	v_cvt_pk_bf16_f32 v98, v110, v111
	v_cvt_pk_bf16_f32 v99, v112, v113
	global_store_dwordx4 v[116:117], v[98:101], off offset:256
	v_cvt_pk_bf16_f32 v88, v82, v83
	v_cvt_pk_bf16_f32 v70, v70, v71
	v_cvt_pk_bf16_f32 v71, v72, v73
	v_cvt_pk_bf16_f32 v72, v58, v59
	v_cvt_pk_bf16_f32 v89, v84, v85
	s_nop 1
	v_or_b32_e32 v100, 32, v132
	v_or_b32_e32 v98, 48, v132
	v_ashrrev_i32_e32 v101, 31, v100
	v_ashrrev_i32_e32 v99, 31, v98
	v_lshlrev_b64 v[82:83], 11, v[100:101]
	v_lshl_add_u64 v[82:83], s[2:3], 0, v[82:83]
	v_lshlrev_b64 v[58:59], 11, v[98:99]
	v_lshl_add_u64 v[100:101], v[82:83], 0, v[114:115]
	v_cvt_pk_bf16_f32 v82, v94, v95
	v_cvt_pk_bf16_f32 v83, v96, v97
	v_lshl_add_u64 v[58:59], s[2:3], 0, v[58:59]
	v_cvt_pk_bf16_f32 v84, v90, v91
	v_cvt_pk_bf16_f32 v85, v92, v93
	global_store_dwordx4 v[100:101], v[82:85], off offset:256
	v_cvt_pk_bf16_f32 v73, v60, v61
	v_cvt_pk_bf16_f32 v46, v46, v47
	v_cvt_pk_bf16_f32 v47, v48, v49
	v_cvt_pk_bf16_f32 v49, v40, v41
	v_cvt_pk_bf16_f32 v40, v34, v35
	s_nop 1
	v_lshl_add_u64 v[82:83], v[58:59], 0, v[114:115]
	global_store_dwordx4 v[82:83], v[70:73], off
	v_cvt_pk_bf16_f32 v41, v36, v37
	v_add_u32_e32 v34, 0xb0, v132
	v_add_u32_e32 v36, 0xa0, v132
	v_add_u32_e32 v70, 0x80, v132
	v_add_u32_e32 v72, 0x90, v132
	v_cvt_pk_bf16_f32 v60, v74, v75
	v_ashrrev_i32_e32 v73, 31, v72
	v_ashrrev_i32_e32 v71, 31, v70
	v_ashrrev_i32_e32 v35, 31, v34
	v_ashrrev_i32_e32 v37, 31, v36
	v_cvt_pk_bf16_f32 v58, v78, v79
	v_cvt_pk_bf16_f32 v59, v80, v81
	v_cvt_pk_bf16_f32 v61, v76, v77
	global_store_dwordx4 v[82:83], v[58:61], off offset:256
	v_cvt_pk_bf16_f32 v48, v38, v39
	v_lshlrev_b64 v[38:39], 11, v[72:73]
	v_cvt_pk_bf16_f32 v30, v30, v31
	v_cvt_pk_bf16_f32 v31, v32, v33
	v_cvt_pk_bf16_f32 v32, v22, v23
	s_nop 0
	v_cvt_pk_bf16_f32 v60, v54, v55
	v_lshlrev_b64 v[54:55], 11, v[70:71]
	v_lshlrev_b64 v[22:23], 11, v[36:37]
	v_cvt_pk_bf16_f32 v14, v14, v15
	v_cvt_pk_bf16_f32 v15, v16, v17
	v_cvt_pk_bf16_f32 v16, v6, v7
	v_lshlrev_b64 v[6:7], 11, v[34:35]
	v_lshl_add_u64 v[54:55], s[2:3], 0, v[54:55]
	v_lshl_add_u64 v[38:39], s[2:3], 0, v[38:39]
	v_lshl_add_u64 v[22:23], s[2:3], 0, v[22:23]
	v_lshl_add_u64 v[6:7], s[2:3], 0, v[6:7]
	s_add_i32 s18, s18, s97
	v_cvt_pk_bf16_f32 v58, v66, v67
	v_cvt_pk_bf16_f32 v61, v56, v57
	v_lshl_add_u64 v[66:67], v[54:55], 0, v[114:115]
	v_cvt_pk_bf16_f32 v56, v50, v51
	v_lshl_add_u64 v[50:51], v[38:39], 0, v[114:115]
	v_cvt_pk_bf16_f32 v33, v24, v25
	v_lshl_add_u64 v[36:37], v[22:23], 0, v[114:115]
	v_cvt_pk_bf16_f32 v24, v18, v19
	v_lshl_add_u64 v[18:19], v[6:7], 0, v[114:115]
	s_cmpk_gt_i32 s18, 0x107
	global_store_dwordx4 v[136:137], v[122:125], off
	global_store_dwordx4 v[116:117], v[102:105], off
	global_store_dwordx4 v[100:101], v[86:89], off
	v_cvt_pk_bf16_f32 v59, v68, v69
	global_store_dwordx4 v[66:67], v[58:61], off
	v_cvt_pk_bf16_f32 v54, v62, v63
	v_cvt_pk_bf16_f32 v55, v64, v65
	v_cvt_pk_bf16_f32 v57, v52, v53
	global_store_dwordx4 v[66:67], v[54:57], off offset:256
	global_store_dwordx4 v[50:51], v[46:49], off
	v_cvt_pk_bf16_f32 v38, v42, v43
	v_cvt_pk_bf16_f32 v39, v44, v45
	global_store_dwordx4 v[50:51], v[38:41], off offset:256
	global_store_dwordx4 v[36:37], v[30:33], off
	v_cvt_pk_bf16_f32 v22, v26, v27
	v_cvt_pk_bf16_f32 v23, v28, v29
	v_cvt_pk_bf16_f32 v25, v20, v21
	global_store_dwordx4 v[36:37], v[22:25], off offset:256
	v_cvt_pk_bf16_f32 v17, v8, v9
	global_store_dwordx4 v[18:19], v[14:17], off
	v_cvt_pk_bf16_f32 v6, v10, v11
	v_cvt_pk_bf16_f32 v7, v12, v13
	v_cvt_pk_bf16_f32 v8, v2, v3
	v_cvt_pk_bf16_f32 v9, v4, v5
	global_store_dwordx4 v[18:19], v[6:9], off offset:256
	s_barrier
	s_cbranch_scc1 .LBB0_127

	.amdhsa_kernel _Z9hymba_fwd6Params
		.amdhsa_group_segment_fixed_size 0
		.amdhsa_private_segment_fixed_size 0
		.amdhsa_kernarg_size 520
		.amdhsa_user_sgpr_count 2
		.amdhsa_user_sgpr_dispatch_ptr 0
		.amdhsa_user_sgpr_queue_ptr 0
		.amdhsa_user_sgpr_kernarg_segment_ptr 1
		.amdhsa_user_sgpr_dispatch_id 0
		.amdhsa_user_sgpr_kernarg_preload_length 0
		.amdhsa_user_sgpr_kernarg_preload_offset 0
		.amdhsa_user_sgpr_private_segment_size 0
		.amdhsa_uses_dynamic_stack 0
		.amdhsa_enable_private_segment 0
		.amdhsa_system_sgpr_workgroup_id_x 1
		.amdhsa_system_sgpr_workgroup_id_y 0
		.amdhsa_system_sgpr_workgroup_id_z 0
		.amdhsa_system_sgpr_workgroup_info 0
		.amdhsa_system_vgpr_workitem_id 0
		.amdhsa_next_free_vgpr 248
		.amdhsa_next_free_sgpr 98
		.amdhsa_accum_offset 248
		.amdhsa_reserve_vcc 1
		.amdhsa_float_round_mode_32 0
		.amdhsa_float_round_mode_16_64 0
		.amdhsa_float_denorm_mode_32 3
		.amdhsa_float_denorm_mode_16_64 3
		.amdhsa_dx10_clamp 1
		.amdhsa_ieee_mode 1
		.amdhsa_fp16_overflow 0
		.amdhsa_tg_split 0
		.amdhsa_exception_fp_ieee_invalid_op 0
		.amdhsa_exception_fp_denorm_src 0
		.amdhsa_exception_fp_ieee_div_zero 0
		.amdhsa_exception_fp_ieee_overflow 0
		.amdhsa_exception_fp_ieee_underflow 0
		.amdhsa_exception_fp_ieee_inexact 0
		.amdhsa_exception_int_div_zero 0
	.end_amdhsa_kernel

.Lfunc_end0:
	.size	_Z9hymba_fwd6Params, .Lfunc_end0-_Z9hymba_fwd6Params
	.set _Z9hymba_fwd6Params.num_vgpr, 248
	.set _Z9hymba_fwd6Params.num_agpr, 0
	.set _Z9hymba_fwd6Params.numbered_sgpr, 98
	.set _Z9hymba_fwd6Params.num_named_barrier, 0
	.set _Z9hymba_fwd6Params.private_seg_size, 0
	.set _Z9hymba_fwd6Params.uses_vcc, 1
	.set _Z9hymba_fwd6Params.uses_flat_scratch, 0
	.set _Z9hymba_fwd6Params.has_dyn_sized_stack, 0
	.set _Z9hymba_fwd6Params.has_recursion, 0
	.set _Z9hymba_fwd6Params.has_indirect_call, 0

amdhsa.kernels:
  - .agpr_count:     0
    .args:
      - .offset:         0
        .size:           264
        .value_kind:     by_value
      - .offset:         264
        .size:           4
        .value_kind:     hidden_block_count_x
      - .offset:         268
        .size:           4
        .value_kind:     hidden_block_count_y
      - .offset:         272
        .size:           4
        .value_kind:     hidden_block_count_z
      - .offset:         276
        .size:           2
        .value_kind:     hidden_group_size_x
      - .offset:         278
        .size:           2
        .value_kind:     hidden_group_size_y
      - .offset:         280
        .size:           2
        .value_kind:     hidden_group_size_z
      - .offset:         282
        .size:           2
        .value_kind:     hidden_remainder_x
      - .offset:         284
        .size:           2
        .value_kind:     hidden_remainder_y
      - .offset:         286
        .size:           2
        .value_kind:     hidden_remainder_z
      - .offset:         304
        .size:           8
        .value_kind:     hidden_global_offset_x
      - .offset:         312
        .size:           8
        .value_kind:     hidden_global_offset_y
      - .offset:         320
        .size:           8
        .value_kind:     hidden_global_offset_z
      - .offset:         328
        .size:           2
        .value_kind:     hidden_grid_dims
      - .offset:         384
        .size:           4
        .value_kind:     hidden_dynamic_lds_size
    .group_segment_fixed_size: 0
    .kernarg_segment_align: 8
    .kernarg_segment_size: 520
    .language:       OpenCL C
    .language_version:
      - 2
      - 0
    .max_flat_workgroup_size: 512
    .name:           _Z9hymba_fwd6Params
    .private_segment_fixed_size: 0
    .sgpr_count:     104
    .sgpr_spill_count: 95
    .symbol:         _Z9hymba_fwd6Params.kd
    .uniform_work_group_size: 1
    .uses_dynamic_stack: false
    .vgpr_count:     248
    .vgpr_spill_count: 0
    .wavefront_size: 64
